# gu_bar2
# baseline (speedup 1.0000x reference)
; __device__ __forceinline__ float silu_f(float x) { return x * __builtin_amdgcn_rcpf(1.f + __builtin_amdgcn_exp2f(-1.4426950408889634f * x)); }
; template <int EPI>
; __device__ __forceinline__ void gemm_epi(const GemmArgs& G, const f32x4 (&a)[4][2], int rbase, int cbase, int fq, const float (&ssv)[4]) {
;   const int tn = cbase >> 8;
; #pragma unroll
;   for (int m = 0; m < 4; ++m) {
;     const int row = rbase + m * 16;
;     float rs = 1.f;
;     if constexpr (EPI == EPI_GU || EPI == EPI_EVIN || EPI == EPI_ODIN) rs = rsqrtf(ssv[m] * (1.f / 2048.f) + 1e-6f);
;     if constexpr (EPI == EPI_GU) {
;       const f32x4 gv = a[m][0] * rs, uv = a[m][1] * rs;
;       const int hc = (cbase >> 1) + fq * 4;
;       u32x2 o = {cvtpk(silu_f(gv[0]) * uv[0], silu_f(gv[1]) * uv[1]), cvtpk(silu_f(gv[2]) * uv[2], silu_f(gv[3]) * uv[3])};
;       *reinterpret_cast<u32x2*>(G.d0 + (size_t)(row - G.row0) * DFF + hc) = o;
.LBB0_2558:
	v_readfirstlane_b32 s16, v224
	s_andn2_b32 s16, s16, 63
	s_nop 0
	v_add_u32_e32 v128, s16, v225
	v_mov_b32_e32 v158, 0xbfb8aa3b
	v_and_b32_e32 v129, 15, v128
	v_ashrrev_i32_e32 v135, 2, v128
	v_and_or_b32 v129, v135, 64, v129
	v_lshrrev_b32_e32 v135, 1, v128
	v_and_b32_e32 v135, 0x60, v135
	v_or_b32_e32 v136, s29, v135
	v_lshrrev_b32_e32 v128, 2, v128
	v_ashrrev_i32_e32 v140, 1, v136
	v_and_b32_e32 v136, 12, v128
	v_or_b32_e32 v140, v140, v136
	v_add_u32_e32 v144, s28, v129
	v_subrev_u32_e32 v141, s40, v144
	v_mul_u32_u24_e32 v141, 0x2c00, v141
	v_lshl_add_u32 v141, v140, 1, v141
	v_mov_b32_e32 v160, 1.0
	s_waitcnt vmcnt(8)
	v_fmamk_f32 v162, v139, 0x3a000000, v229
	v_fmamk_f32 v164, v138, 0x3a000000, v229
	v_fmamk_f32 v166, v137, 0x3a000000, v229
	v_fmamk_f32 v168, v134, 0x3a000000, v229
	v_fmamk_f32 v170, v133, 0x3a000000, v229
	v_fmamk_f32 v172, v132, 0x3a000000, v229
	v_fmamk_f32 v174, v131, 0x3a000000, v229
	v_fmamk_f32 v176, v130, 0x3a000000, v229
	v_rsq_f32_e32 v162, v162
	v_rsq_f32_e32 v164, v164
	v_rsq_f32_e32 v166, v166
	v_rsq_f32_e32 v168, v168
	v_rsq_f32_e32 v170, v170
	v_rsq_f32_e32 v172, v172
	v_rsq_f32_e32 v174, v174
	v_rsq_f32_e32 v176, v176
	v_pk_mul_f32 v[120:121], v[162:163], v[120:121] op_sel_hi:[0,1]
	v_pk_mul_f32 v[112:113], v[164:165], v[112:113] op_sel_hi:[0,1]
	v_pk_mul_f32 v[122:123], v[162:163], v[122:123] op_sel_hi:[0,1]
	v_pk_mul_f32 v[114:115], v[164:165], v[114:115] op_sel_hi:[0,1]
	v_pk_mul_f32 v[124:125], v[162:163], v[124:125] op_sel_hi:[0,1]
	v_pk_mul_f32 v[116:117], v[164:165], v[116:117] op_sel_hi:[0,1]
	v_pk_mul_f32 v[126:127], v[162:163], v[126:127] op_sel_hi:[0,1]
	v_pk_mul_f32 v[118:119], v[164:165], v[118:119] op_sel_hi:[0,1]
	v_pk_mul_f32 v[182:183], v[158:159], v[120:121] op_sel_hi:[0,1]
	v_pk_mul_f32 v[186:187], v[158:159], v[112:113] op_sel_hi:[0,1]
	v_pk_mul_f32 v[184:185], v[158:159], v[122:123] op_sel_hi:[0,1]
	v_pk_mul_f32 v[188:189], v[158:159], v[114:115] op_sel_hi:[0,1]
	v_exp_f32_e32 v182, v182
	v_exp_f32_e32 v186, v186
	v_exp_f32_e32 v183, v183
	v_exp_f32_e32 v187, v187
	v_exp_f32_e32 v184, v184
	v_exp_f32_e32 v188, v188
	v_exp_f32_e32 v185, v185
	v_exp_f32_e32 v189, v189
	v_pk_add_f32 v[182:183], v[160:161], v[182:183] op_sel_hi:[0,1]
	v_pk_add_f32 v[186:187], v[160:161], v[186:187] op_sel_hi:[0,1]
	v_pk_add_f32 v[184:185], v[160:161], v[184:185] op_sel_hi:[0,1]
	v_pk_add_f32 v[188:189], v[160:161], v[188:189] op_sel_hi:[0,1]
	v_rcp_f32_e32 v182, v182
	v_rcp_f32_e32 v186, v186
	v_rcp_f32_e32 v183, v183
	v_rcp_f32_e32 v187, v187
	v_rcp_f32_e32 v184, v184
	v_rcp_f32_e32 v188, v188
	v_rcp_f32_e32 v185, v185
	v_rcp_f32_e32 v189, v189
	v_pk_mul_f32 v[120:121], v[120:121], v[182:183]
	v_pk_mul_f32 v[112:113], v[112:113], v[186:187]
	v_pk_mul_f32 v[122:123], v[122:123], v[184:185]
	v_pk_mul_f32 v[114:115], v[114:115], v[188:189]
	v_pk_mul_f32 v[120:121], v[124:125], v[120:121]
	v_pk_mul_f32 v[112:113], v[116:117], v[112:113]
	v_pk_mul_f32 v[122:123], v[126:127], v[122:123]
	v_pk_mul_f32 v[114:115], v[118:119], v[114:115]
	v_cvt_pk_bf16_f32 v200, v120, v121
	v_cvt_pk_bf16_f32 v202, v112, v113
	v_cvt_pk_bf16_f32 v201, v122, v123
	v_cvt_pk_bf16_f32 v203, v114, v115
	v_mov_b32_e32 v210, v141
	v_add_u32_e32 v211, 0x2c000, v141
	global_store_dwordx2 v210, v[200:201], s[10:11]
	global_store_dwordx2 v211, v[202:203], s[10:11]
	v_pk_mul_f32 v[104:105], v[166:167], v[104:105] op_sel_hi:[0,1]
	v_pk_mul_f32 v[96:97], v[168:169], v[96:97] op_sel_hi:[0,1]
	v_pk_mul_f32 v[106:107], v[166:167], v[106:107] op_sel_hi:[0,1]
	v_pk_mul_f32 v[98:99], v[168:169], v[98:99] op_sel_hi:[0,1]
	v_pk_mul_f32 v[108:109], v[166:167], v[108:109] op_sel_hi:[0,1]
	v_pk_mul_f32 v[100:101], v[168:169], v[100:101] op_sel_hi:[0,1]
	v_pk_mul_f32 v[110:111], v[166:167], v[110:111] op_sel_hi:[0,1]
	v_pk_mul_f32 v[102:103], v[168:169], v[102:103] op_sel_hi:[0,1]
	v_pk_mul_f32 v[190:191], v[158:159], v[104:105] op_sel_hi:[0,1]
	v_pk_mul_f32 v[194:195], v[158:159], v[96:97] op_sel_hi:[0,1]
	v_pk_mul_f32 v[192:193], v[158:159], v[106:107] op_sel_hi:[0,1]
	v_pk_mul_f32 v[196:197], v[158:159], v[98:99] op_sel_hi:[0,1]
	v_exp_f32_e32 v190, v190
	v_exp_f32_e32 v194, v194
	v_exp_f32_e32 v191, v191
	v_exp_f32_e32 v195, v195
	v_exp_f32_e32 v192, v192
	v_exp_f32_e32 v196, v196
	v_exp_f32_e32 v193, v193
	v_exp_f32_e32 v197, v197
	v_pk_add_f32 v[190:191], v[160:161], v[190:191] op_sel_hi:[0,1]
	v_pk_add_f32 v[194:195], v[160:161], v[194:195] op_sel_hi:[0,1]
	v_pk_add_f32 v[192:193], v[160:161], v[192:193] op_sel_hi:[0,1]
	v_pk_add_f32 v[196:197], v[160:161], v[196:197] op_sel_hi:[0,1]
	v_rcp_f32_e32 v190, v190
	v_rcp_f32_e32 v194, v194
	v_rcp_f32_e32 v191, v191
	v_rcp_f32_e32 v195, v195
	v_rcp_f32_e32 v192, v192
	v_rcp_f32_e32 v196, v196
	v_rcp_f32_e32 v193, v193
	v_rcp_f32_e32 v197, v197
	v_pk_mul_f32 v[104:105], v[104:105], v[190:191]
	v_pk_mul_f32 v[96:97], v[96:97], v[194:195]
	v_pk_mul_f32 v[106:107], v[106:107], v[192:193]
	v_pk_mul_f32 v[98:99], v[98:99], v[196:197]
	v_pk_mul_f32 v[104:105], v[108:109], v[104:105]
	v_pk_mul_f32 v[96:97], v[100:101], v[96:97]
	v_pk_mul_f32 v[106:107], v[110:111], v[106:107]
	v_pk_mul_f32 v[98:99], v[102:103], v[98:99]
	v_cvt_pk_bf16_f32 v204, v104, v105
	v_cvt_pk_bf16_f32 v206, v96, v97
	v_cvt_pk_bf16_f32 v205, v106, v107
	v_cvt_pk_bf16_f32 v207, v98, v99
	v_add_u32_e32 v212, 0x58000, v141
	v_add_u32_e32 v213, 0x84000, v141
	global_store_dwordx2 v212, v[204:205], s[10:11]
	global_store_dwordx2 v213, v[206:207], s[10:11]
	v_pk_mul_f32 v[88:89], v[162:163], v[88:89] op_sel_hi:[0,1]
	v_pk_mul_f32 v[80:81], v[164:165], v[80:81] op_sel_hi:[0,1]
	v_pk_mul_f32 v[90:91], v[162:163], v[90:91] op_sel_hi:[0,1]
; __device__ __forceinline__ float silu_f(float x) { return x * __builtin_amdgcn_rcpf(1.f + __builtin_amdgcn_exp2f(-1.4426950408889634f * x)); }
; template <int EPI>
; __device__ __forceinline__ void gemm_epi(const GemmArgs& G, const f32x4 (&a)[4][2], int rbase, int cbase, int fq, const float (&ssv)[4]) {
;   const int tn = cbase >> 8;
; #pragma unroll
;   for (int m = 0; m < 4; ++m) {
;     const int row = rbase + m * 16;
;     float rs = 1.f;
;     if constexpr (EPI == EPI_GU || EPI == EPI_EVIN || EPI == EPI_ODIN) rs = rsqrtf(ssv[m] * (1.f / 2048.f) + 1e-6f);
;     if constexpr (EPI == EPI_GU) {
;       const f32x4 gv = a[m][0] * rs, uv = a[m][1] * rs;
;       const int hc = (cbase >> 1) + fq * 4;
;       u32x2 o = {cvtpk(silu_f(gv[0]) * uv[0], silu_f(gv[1]) * uv[1]), cvtpk(silu_f(gv[2]) * uv[2], silu_f(gv[3]) * uv[3])};
;       *reinterpret_cast<u32x2*>(G.d0 + (size_t)(row - G.row0) * DFF + hc) = o;
	v_pk_mul_f32 v[82:83], v[164:165], v[82:83] op_sel_hi:[0,1]
	v_pk_mul_f32 v[92:93], v[162:163], v[92:93] op_sel_hi:[0,1]
	v_pk_mul_f32 v[84:85], v[164:165], v[84:85] op_sel_hi:[0,1]
	v_pk_mul_f32 v[94:95], v[162:163], v[94:95] op_sel_hi:[0,1]
	v_pk_mul_f32 v[86:87], v[164:165], v[86:87] op_sel_hi:[0,1]
	v_pk_mul_f32 v[182:183], v[158:159], v[88:89] op_sel_hi:[0,1]
	v_pk_mul_f32 v[186:187], v[158:159], v[80:81] op_sel_hi:[0,1]
	v_pk_mul_f32 v[184:185], v[158:159], v[90:91] op_sel_hi:[0,1]
	v_pk_mul_f32 v[188:189], v[158:159], v[82:83] op_sel_hi:[0,1]
	v_exp_f32_e32 v182, v182
	v_exp_f32_e32 v186, v186
	v_exp_f32_e32 v183, v183
	v_exp_f32_e32 v187, v187
	v_exp_f32_e32 v184, v184
	v_exp_f32_e32 v188, v188
	v_exp_f32_e32 v185, v185
	v_exp_f32_e32 v189, v189
	v_pk_add_f32 v[182:183], v[160:161], v[182:183] op_sel_hi:[0,1]
	v_pk_add_f32 v[186:187], v[160:161], v[186:187] op_sel_hi:[0,1]
	v_pk_add_f32 v[184:185], v[160:161], v[184:185] op_sel_hi:[0,1]
	v_pk_add_f32 v[188:189], v[160:161], v[188:189] op_sel_hi:[0,1]
	v_rcp_f32_e32 v182, v182
	v_rcp_f32_e32 v186, v186
	v_rcp_f32_e32 v183, v183
	v_rcp_f32_e32 v187, v187
	v_rcp_f32_e32 v184, v184
	v_rcp_f32_e32 v188, v188
	v_rcp_f32_e32 v185, v185
	v_rcp_f32_e32 v189, v189
	v_pk_mul_f32 v[88:89], v[88:89], v[182:183]
	v_pk_mul_f32 v[80:81], v[80:81], v[186:187]
	v_pk_mul_f32 v[90:91], v[90:91], v[184:185]
	v_pk_mul_f32 v[82:83], v[82:83], v[188:189]
	v_pk_mul_f32 v[88:89], v[92:93], v[88:89]
	v_pk_mul_f32 v[80:81], v[84:85], v[80:81]
	v_pk_mul_f32 v[90:91], v[94:95], v[90:91]
	v_pk_mul_f32 v[82:83], v[86:87], v[82:83]
	v_cvt_pk_bf16_f32 v200, v88, v89
	v_cvt_pk_bf16_f32 v202, v80, v81
	v_cvt_pk_bf16_f32 v201, v90, v91
	v_cvt_pk_bf16_f32 v203, v82, v83
	v_add_u32_e32 v210, 0x80, v141
	v_add_u32_e32 v211, 0x2c080, v141
	global_store_dwordx2 v210, v[200:201], s[10:11]
	global_store_dwordx2 v211, v[202:203], s[10:11]
	v_pk_mul_f32 v[72:73], v[166:167], v[72:73] op_sel_hi:[0,1]
	v_pk_mul_f32 v[64:65], v[168:169], v[64:65] op_sel_hi:[0,1]
	v_pk_mul_f32 v[74:75], v[166:167], v[74:75] op_sel_hi:[0,1]
	v_pk_mul_f32 v[66:67], v[168:169], v[66:67] op_sel_hi:[0,1]
	v_pk_mul_f32 v[76:77], v[166:167], v[76:77] op_sel_hi:[0,1]
	v_pk_mul_f32 v[68:69], v[168:169], v[68:69] op_sel_hi:[0,1]
	v_pk_mul_f32 v[78:79], v[166:167], v[78:79] op_sel_hi:[0,1]
	v_pk_mul_f32 v[70:71], v[168:169], v[70:71] op_sel_hi:[0,1]
	v_pk_mul_f32 v[190:191], v[158:159], v[72:73] op_sel_hi:[0,1]
	v_pk_mul_f32 v[194:195], v[158:159], v[64:65] op_sel_hi:[0,1]
	v_pk_mul_f32 v[192:193], v[158:159], v[74:75] op_sel_hi:[0,1]
	v_pk_mul_f32 v[196:197], v[158:159], v[66:67] op_sel_hi:[0,1]
	v_exp_f32_e32 v190, v190
	v_exp_f32_e32 v194, v194
	v_exp_f32_e32 v191, v191
	v_exp_f32_e32 v195, v195
	v_exp_f32_e32 v192, v192
	v_exp_f32_e32 v196, v196
	v_exp_f32_e32 v193, v193
	v_exp_f32_e32 v197, v197
	v_pk_add_f32 v[190:191], v[160:161], v[190:191] op_sel_hi:[0,1]
	v_pk_add_f32 v[194:195], v[160:161], v[194:195] op_sel_hi:[0,1]
	v_pk_add_f32 v[192:193], v[160:161], v[192:193] op_sel_hi:[0,1]
	v_pk_add_f32 v[196:197], v[160:161], v[196:197] op_sel_hi:[0,1]
	v_rcp_f32_e32 v190, v190
	v_rcp_f32_e32 v194, v194
	v_rcp_f32_e32 v191, v191
	v_rcp_f32_e32 v195, v195
	v_rcp_f32_e32 v192, v192
	v_rcp_f32_e32 v196, v196
	v_rcp_f32_e32 v193, v193
	v_rcp_f32_e32 v197, v197
	v_pk_mul_f32 v[72:73], v[72:73], v[190:191]
	v_pk_mul_f32 v[64:65], v[64:65], v[194:195]
	v_pk_mul_f32 v[74:75], v[74:75], v[192:193]
	v_pk_mul_f32 v[66:67], v[66:67], v[196:197]
	v_pk_mul_f32 v[72:73], v[76:77], v[72:73]
	v_pk_mul_f32 v[64:65], v[68:69], v[64:65]
	v_pk_mul_f32 v[74:75], v[78:79], v[74:75]
	v_pk_mul_f32 v[66:67], v[70:71], v[66:67]
	v_cvt_pk_bf16_f32 v204, v72, v73
	v_cvt_pk_bf16_f32 v206, v64, v65
	v_cvt_pk_bf16_f32 v205, v74, v75
	v_cvt_pk_bf16_f32 v207, v66, v67
	v_add_u32_e32 v212, 0x58080, v141
	v_add_u32_e32 v213, 0x84080, v141
	global_store_dwordx2 v212, v[204:205], s[10:11]
	global_store_dwordx2 v213, v[206:207], s[10:11]
	v_pk_mul_f32 v[56:57], v[170:171], v[56:57] op_sel_hi:[0,1]
	v_pk_mul_f32 v[48:49], v[172:173], v[48:49] op_sel_hi:[0,1]
	v_pk_mul_f32 v[58:59], v[170:171], v[58:59] op_sel_hi:[0,1]
	v_pk_mul_f32 v[50:51], v[172:173], v[50:51] op_sel_hi:[0,1]
	v_pk_mul_f32 v[60:61], v[170:171], v[60:61] op_sel_hi:[0,1]
	v_pk_mul_f32 v[52:53], v[172:173], v[52:53] op_sel_hi:[0,1]
	v_pk_mul_f32 v[62:63], v[170:171], v[62:63] op_sel_hi:[0,1]
	v_pk_mul_f32 v[54:55], v[172:173], v[54:55] op_sel_hi:[0,1]
	v_pk_mul_f32 v[182:183], v[158:159], v[56:57] op_sel_hi:[0,1]
	v_pk_mul_f32 v[186:187], v[158:159], v[48:49] op_sel_hi:[0,1]
	v_pk_mul_f32 v[184:185], v[158:159], v[58:59] op_sel_hi:[0,1]
	v_pk_mul_f32 v[188:189], v[158:159], v[50:51] op_sel_hi:[0,1]
	v_exp_f32_e32 v182, v182
	v_exp_f32_e32 v186, v186
	v_exp_f32_e32 v183, v183
	v_exp_f32_e32 v187, v187
	v_exp_f32_e32 v184, v184
	v_exp_f32_e32 v188, v188
	v_exp_f32_e32 v185, v185
	v_exp_f32_e32 v189, v189
	v_pk_add_f32 v[182:183], v[160:161], v[182:183] op_sel_hi:[0,1]
	v_pk_add_f32 v[186:187], v[160:161], v[186:187] op_sel_hi:[0,1]
	v_pk_add_f32 v[184:185], v[160:161], v[184:185] op_sel_hi:[0,1]
	v_pk_add_f32 v[188:189], v[160:161], v[188:189] op_sel_hi:[0,1]
	v_rcp_f32_e32 v182, v182
	v_rcp_f32_e32 v186, v186
	v_rcp_f32_e32 v183, v183
	v_rcp_f32_e32 v187, v187
	v_rcp_f32_e32 v184, v184
	v_rcp_f32_e32 v188, v188
	v_rcp_f32_e32 v185, v185
	v_rcp_f32_e32 v189, v189
	v_pk_mul_f32 v[56:57], v[56:57], v[182:183]
	v_pk_mul_f32 v[48:49], v[48:49], v[186:187]
	v_pk_mul_f32 v[58:59], v[58:59], v[184:185]
	v_pk_mul_f32 v[50:51], v[50:51], v[188:189]
	v_pk_mul_f32 v[56:57], v[60:61], v[56:57]
	v_pk_mul_f32 v[48:49], v[52:53], v[48:49]
; __device__ __forceinline__ float silu_f(float x) { return x * __builtin_amdgcn_rcpf(1.f + __builtin_amdgcn_exp2f(-1.4426950408889634f * x)); }
; #define BAR __builtin_amdgcn_s_barrier()
; template <int EPI>
; __device__ __forceinline__ void gemm_epi(const GemmArgs& G, const f32x4 (&a)[4][2], int rbase, int cbase, int fq, const float (&ssv)[4]) {
;     ...
;   for (int m = 0; m < 4; ++m) {
;     const int row = rbase + m * 16;
;     float rs = 1.f;
;     if constexpr (EPI == EPI_GU || EPI == EPI_EVIN || EPI == EPI_ODIN) rs = rsqrtf(ssv[m] * (1.f / 2048.f) + 1e-6f);
;     if constexpr (EPI == EPI_GU) {
;       const f32x4 gv = a[m][0] * rs, uv = a[m][1] * rs;
;       const int hc = (cbase >> 1) + fq * 4;
;       u32x2 o = {cvtpk(silu_f(gv[0]) * uv[0], silu_f(gv[1]) * uv[1]), cvtpk(silu_f(gv[2]) * uv[2], silu_f(gv[3]) * uv[3])};
;       *reinterpret_cast<u32x2*>(G.d0 + (size_t)(row - G.row0) * DFF + hc) = o;
;     ...
;   if (wr == 0) BAR;
	v_pk_mul_f32 v[58:59], v[62:63], v[58:59]
	v_pk_mul_f32 v[50:51], v[54:55], v[50:51]
	v_cvt_pk_bf16_f32 v200, v56, v57
	v_cvt_pk_bf16_f32 v202, v48, v49
	v_cvt_pk_bf16_f32 v201, v58, v59
	v_cvt_pk_bf16_f32 v203, v50, v51
	v_add_u32_e32 v210, 0x160000, v141
	v_add_u32_e32 v211, 0x18c000, v141
	global_store_dwordx2 v210, v[200:201], s[10:11]
	global_store_dwordx2 v211, v[202:203], s[10:11]
	v_pk_mul_f32 v[40:41], v[174:175], v[40:41] op_sel_hi:[0,1]
	v_pk_mul_f32 v[32:33], v[176:177], v[32:33] op_sel_hi:[0,1]
	v_pk_mul_f32 v[42:43], v[174:175], v[42:43] op_sel_hi:[0,1]
	v_pk_mul_f32 v[34:35], v[176:177], v[34:35] op_sel_hi:[0,1]
	v_pk_mul_f32 v[44:45], v[174:175], v[44:45] op_sel_hi:[0,1]
	v_pk_mul_f32 v[36:37], v[176:177], v[36:37] op_sel_hi:[0,1]
	v_pk_mul_f32 v[46:47], v[174:175], v[46:47] op_sel_hi:[0,1]
	v_pk_mul_f32 v[38:39], v[176:177], v[38:39] op_sel_hi:[0,1]
	v_pk_mul_f32 v[190:191], v[158:159], v[40:41] op_sel_hi:[0,1]
	v_pk_mul_f32 v[194:195], v[158:159], v[32:33] op_sel_hi:[0,1]
	v_pk_mul_f32 v[192:193], v[158:159], v[42:43] op_sel_hi:[0,1]
	v_pk_mul_f32 v[196:197], v[158:159], v[34:35] op_sel_hi:[0,1]
	v_exp_f32_e32 v190, v190
	v_exp_f32_e32 v194, v194
	v_exp_f32_e32 v191, v191
	v_exp_f32_e32 v195, v195
	v_exp_f32_e32 v192, v192
	v_exp_f32_e32 v196, v196
	v_exp_f32_e32 v193, v193
	v_exp_f32_e32 v197, v197
	v_pk_add_f32 v[190:191], v[160:161], v[190:191] op_sel_hi:[0,1]
	v_pk_add_f32 v[194:195], v[160:161], v[194:195] op_sel_hi:[0,1]
	v_pk_add_f32 v[192:193], v[160:161], v[192:193] op_sel_hi:[0,1]
	v_pk_add_f32 v[196:197], v[160:161], v[196:197] op_sel_hi:[0,1]
	v_rcp_f32_e32 v190, v190
	v_rcp_f32_e32 v194, v194
	v_rcp_f32_e32 v191, v191
	v_rcp_f32_e32 v195, v195
	v_rcp_f32_e32 v192, v192
	v_rcp_f32_e32 v196, v196
	v_rcp_f32_e32 v193, v193
	v_rcp_f32_e32 v197, v197
	v_pk_mul_f32 v[40:41], v[40:41], v[190:191]
	v_pk_mul_f32 v[32:33], v[32:33], v[194:195]
	v_pk_mul_f32 v[42:43], v[42:43], v[192:193]
	v_pk_mul_f32 v[34:35], v[34:35], v[196:197]
	v_pk_mul_f32 v[40:41], v[44:45], v[40:41]
	v_pk_mul_f32 v[32:33], v[36:37], v[32:33]
	v_pk_mul_f32 v[42:43], v[46:47], v[42:43]
	v_pk_mul_f32 v[34:35], v[38:39], v[34:35]
	v_cvt_pk_bf16_f32 v204, v40, v41
	v_cvt_pk_bf16_f32 v206, v32, v33
	v_cvt_pk_bf16_f32 v205, v42, v43
	v_cvt_pk_bf16_f32 v207, v34, v35
	v_add_u32_e32 v212, 0x1b8000, v141
	v_add_u32_e32 v213, 0x1e4000, v141
	global_store_dwordx2 v212, v[204:205], s[10:11]
	global_store_dwordx2 v213, v[206:207], s[10:11]
	v_pk_mul_f32 v[24:25], v[170:171], v[24:25] op_sel_hi:[0,1]
	v_pk_mul_f32 v[16:17], v[172:173], v[16:17] op_sel_hi:[0,1]
	v_pk_mul_f32 v[26:27], v[170:171], v[26:27] op_sel_hi:[0,1]
	v_pk_mul_f32 v[18:19], v[172:173], v[18:19] op_sel_hi:[0,1]
	v_pk_mul_f32 v[28:29], v[170:171], v[28:29] op_sel_hi:[0,1]
	v_pk_mul_f32 v[20:21], v[172:173], v[20:21] op_sel_hi:[0,1]
	v_pk_mul_f32 v[30:31], v[170:171], v[30:31] op_sel_hi:[0,1]
	v_pk_mul_f32 v[22:23], v[172:173], v[22:23] op_sel_hi:[0,1]
	v_pk_mul_f32 v[182:183], v[158:159], v[24:25] op_sel_hi:[0,1]
	v_pk_mul_f32 v[186:187], v[158:159], v[16:17] op_sel_hi:[0,1]
	v_pk_mul_f32 v[184:185], v[158:159], v[26:27] op_sel_hi:[0,1]
	v_pk_mul_f32 v[188:189], v[158:159], v[18:19] op_sel_hi:[0,1]
	v_exp_f32_e32 v182, v182
	v_exp_f32_e32 v186, v186
	v_exp_f32_e32 v183, v183
	v_exp_f32_e32 v187, v187
	v_exp_f32_e32 v184, v184
	v_exp_f32_e32 v188, v188
	v_exp_f32_e32 v185, v185
	v_exp_f32_e32 v189, v189
	v_pk_add_f32 v[182:183], v[160:161], v[182:183] op_sel_hi:[0,1]
	v_pk_add_f32 v[186:187], v[160:161], v[186:187] op_sel_hi:[0,1]
	v_pk_add_f32 v[184:185], v[160:161], v[184:185] op_sel_hi:[0,1]
	v_pk_add_f32 v[188:189], v[160:161], v[188:189] op_sel_hi:[0,1]
	v_rcp_f32_e32 v182, v182
	v_rcp_f32_e32 v186, v186
	v_rcp_f32_e32 v183, v183
	v_rcp_f32_e32 v187, v187
	v_rcp_f32_e32 v184, v184
	v_rcp_f32_e32 v188, v188
	v_rcp_f32_e32 v185, v185
	v_rcp_f32_e32 v189, v189
	v_pk_mul_f32 v[24:25], v[24:25], v[182:183]
	v_pk_mul_f32 v[16:17], v[16:17], v[186:187]
	v_pk_mul_f32 v[26:27], v[26:27], v[184:185]
	v_pk_mul_f32 v[18:19], v[18:19], v[188:189]
	v_pk_mul_f32 v[24:25], v[28:29], v[24:25]
	v_pk_mul_f32 v[16:17], v[20:21], v[16:17]
	v_pk_mul_f32 v[26:27], v[30:31], v[26:27]
	v_pk_mul_f32 v[18:19], v[22:23], v[18:19]
	v_cvt_pk_bf16_f32 v200, v24, v25
	v_cvt_pk_bf16_f32 v202, v16, v17
	v_cvt_pk_bf16_f32 v201, v26, v27
	v_cvt_pk_bf16_f32 v203, v18, v19
	v_add_u32_e32 v210, 0x160080, v141
	v_add_u32_e32 v211, 0x18c080, v141
	global_store_dwordx2 v210, v[200:201], s[10:11]
	global_store_dwordx2 v211, v[202:203], s[10:11]
	v_pk_mul_f32 v[8:9], v[174:175], v[8:9] op_sel_hi:[0,1]
	v_pk_mul_f32 v[0:1], v[176:177], v[0:1] op_sel_hi:[0,1]
	v_pk_mul_f32 v[10:11], v[174:175], v[10:11] op_sel_hi:[0,1]
	v_pk_mul_f32 v[2:3], v[176:177], v[2:3] op_sel_hi:[0,1]
	v_pk_mul_f32 v[12:13], v[174:175], v[12:13] op_sel_hi:[0,1]
	v_pk_mul_f32 v[4:5], v[176:177], v[4:5] op_sel_hi:[0,1]
	v_pk_mul_f32 v[14:15], v[174:175], v[14:15] op_sel_hi:[0,1]
	v_pk_mul_f32 v[6:7], v[176:177], v[6:7] op_sel_hi:[0,1]
	v_pk_mul_f32 v[190:191], v[158:159], v[8:9] op_sel_hi:[0,1]
	v_pk_mul_f32 v[194:195], v[158:159], v[0:1] op_sel_hi:[0,1]
	v_pk_mul_f32 v[192:193], v[158:159], v[10:11] op_sel_hi:[0,1]
	v_pk_mul_f32 v[196:197], v[158:159], v[2:3] op_sel_hi:[0,1]
	v_exp_f32_e32 v190, v190
	v_exp_f32_e32 v194, v194
	v_exp_f32_e32 v191, v191
	v_exp_f32_e32 v195, v195
	v_exp_f32_e32 v192, v192
	v_exp_f32_e32 v196, v196
	v_exp_f32_e32 v193, v193
	v_exp_f32_e32 v197, v197
	v_pk_add_f32 v[190:191], v[160:161], v[190:191] op_sel_hi:[0,1]
	v_pk_add_f32 v[194:195], v[160:161], v[194:195] op_sel_hi:[0,1]
	v_pk_add_f32 v[192:193], v[160:161], v[192:193] op_sel_hi:[0,1]
	v_pk_add_f32 v[196:197], v[160:161], v[196:197] op_sel_hi:[0,1]
	v_rcp_f32_e32 v190, v190
	v_rcp_f32_e32 v194, v194
	v_rcp_f32_e32 v191, v191
	v_rcp_f32_e32 v195, v195
	v_rcp_f32_e32 v192, v192
	v_rcp_f32_e32 v196, v196
	v_rcp_f32_e32 v193, v193
	v_rcp_f32_e32 v197, v197
	v_pk_mul_f32 v[8:9], v[8:9], v[190:191]
	v_pk_mul_f32 v[0:1], v[0:1], v[194:195]
	v_pk_mul_f32 v[10:11], v[10:11], v[192:193]
	v_pk_mul_f32 v[2:3], v[2:3], v[196:197]
	v_pk_mul_f32 v[8:9], v[12:13], v[8:9]
	v_pk_mul_f32 v[0:1], v[4:5], v[0:1]
	v_pk_mul_f32 v[10:11], v[14:15], v[10:11]
	v_pk_mul_f32 v[2:3], v[6:7], v[2:3]
	v_cvt_pk_bf16_f32 v204, v8, v9
	v_cvt_pk_bf16_f32 v206, v0, v1
	v_cvt_pk_bf16_f32 v205, v10, v11
	v_cvt_pk_bf16_f32 v207, v2, v3
	v_add_u32_e32 v212, 0x1b8080, v141
	v_add_u32_e32 v213, 0x1e4080, v141
	global_store_dwordx2 v212, v[204:205], s[10:11]
	global_store_dwordx2 v213, v[206:207], s[10:11]
	s_barrier
	s_andn2_b64 vcc, exec, s[14:15]
	s_mov_b32 s18, s25
	s_cbranch_vccz .LBB0_2571

; #define STAGE_A(P, br, kt) do { const char* _base = (const char*)(((kt) < G.ksplit ? G.A1 : A2m) + (long)(br) * G.lda + (long)(kt) * BK); \
;     __builtin_amdgcn_global_load_lds((const unsigned*)(_base + aoff0), (unsigned*)((char*)(P) + sb0), 16, 0, 0); \
;     __builtin_amdgcn_global_load_lds((const unsigned*)(_base + aoff1), (unsigned*)((char*)(P) + sb1), 16, 0, 0); } while (0)
; #define LDA(dst, b, h) for (int m = 0; m < 4; ++m) for (int k = 0; k < 2; ++k) \
;     dst[m][k] = *reinterpret_cast<const bf16x8*>(a_rd + ((b) * 2 + (h)) * (HT * 2) + m * 2048 + k * 1024)
; #define LDB(dst, b, h) for (int n = 0; n < 2; ++n) for (int k = 0; k < 2; ++k) \
;     dst[n][k] = *reinterpret_cast<const bf16x8*>(b_rd + ((b) * 2 + (h)) * (HT * 2) + n * 2048 + k * 1024)
; #define MMA(ai, bj, At_, Bt_) do { __builtin_amdgcn_s_setprio(1); \
;     for (int m = 0; m < 4; ++m) for (int n = 0; n < 2; ++n) for (int k = 0; k < 2; ++k) \
;       acc[ai][bj][m][n] = __builtin_amdgcn_mfma_f32_16x16x32_bf16(Bt_[n][k], At_[m][k], acc[ai][bj][m][n], 0, 0, 0); \
;     __builtin_amdgcn_s_setprio(0); } while (0)
; #define WAIT_V(n) asm volatile("s_waitcnt vmcnt(" #n ")" ::: "memory")
; #define WAIT_L(n) asm volatile("s_waitcnt lgkmcnt(" #n ")" ::: "memory")
; #define BAR __builtin_amdgcn_s_barrier()
;     ...
;   float ssv[2][4] = {};
;   if constexpr (EPI == EPI_GU || EPI == EPI_EVIN || EPI == EPI_ODIN) {
; #pragma unroll
;     for (int ai = 0; ai < 2; ++ai)
; #pragma unroll
;       for (int m = 0; m < 4; ++m) ssv[ai][m] = G.ssr[brow + ai * HALF + wr * 64 + m * 16 + fr];
;   }
;   { LDB(B0, 0, 0); LDA(At, 0, 0); STAGE_A(SA(1, 1), brow + HALF, nt - 1);
;     BAR; WAIT_L(0); MMA(0, 0, At, B0); BAR;
;     LDB(B1, 0, 1); BAR; WAIT_L(0); MMA(0, 1, At, B1); BAR;
;     LDA(At, 0, 1); WAIT_V(4); BAR; WAIT_L(0); MMA(1, 0, At, B0); MMA(1, 1, At, B1); BAR; }
.Lmy_kexit_4:
	s_waitcnt vmcnt(6)
	v_not_b32_e32 v250, 63
	v_mov_b32_e32 v251, 0x41b17218
	v_or_b32_e32 v130, s28, v152
	v_lshl_add_u32 v130, v151, 6, v130
	v_add_u32_e32 v134, 0x80, v130
	v_ashrrev_i32_e32 v135, 31, v134
	v_lshl_add_u64 v[140:141], v[134:135], 2, s[12:13]
	v_add_u32_e32 v134, 0x90, v130
	v_ashrrev_i32_e32 v131, 31, v130
	v_ashrrev_i32_e32 v135, 31, v134
	v_lshl_add_u64 v[132:133], v[130:131], 2, s[12:13]
	v_lshl_add_u64 v[152:153], v[134:135], 2, s[12:13]
	v_add_u32_e32 v134, 0xa0, v130
	v_add_u32_e32 v130, 0xb0, v130
	s_or_b32 s21, s28, 0x80
	v_ashrrev_i32_e32 v135, 31, v134
	v_ashrrev_i32_e32 v131, 31, v130
	s_mul_i32 s18, s21, 0x1080
	v_lshl_add_u64 v[154:155], v[134:135], 2, s[12:13]
	v_lshl_add_u64 v[156:157], v[130:131], 2, s[12:13]
	global_load_dword v139, v[132:133], off
	global_load_dword v138, v[132:133], off offset:64
	global_load_dword v137, v[132:133], off offset:128
	global_load_dword v134, v[132:133], off offset:192
	s_nop 0
	global_load_dword v133, v[140:141], off
	global_load_dword v132, v[152:153], off
	global_load_dword v131, v[154:155], off
	global_load_dword v130, v[156:157], off
	s_mul_hi_i32 s19, s21, 0x1080
	s_add_u32 s18, s23, s18
	s_addc_u32 s19, s24, s19
	v_lshl_add_u64 v[140:141], s[18:19], 0, v[180:181]
	v_readfirstlane_b32 s31, v162
	v_lshl_add_u64 v[140:141], v[140:141], 0, s[46:47]
	s_mov_b32 m0, s31
	ds_read_b128 v[152:155], v150
	ds_read_b128 v[164:167], v150 offset:1024
	ds_read_b128 v[168:171], v150 offset:2048
	ds_read_b128 v[172:175], v150 offset:3072
	ds_read_b128 v[176:179], v149
	ds_read_b128 v[182:185], v149 offset:1024
	ds_read_b128 v[186:189], v149 offset:2048
	ds_read_b128 v[190:193], v149 offset:3072
	ds_read_b128 v[194:197], v149 offset:4096
	ds_read_b128 v[198:201], v149 offset:5120
	ds_read_b128 v[202:205], v149 offset:6144
	ds_read_b128 v[206:209], v149 offset:7168
	global_load_lds_dwordx4 v[140:141], off
	v_lshl_add_u64 v[140:141], s[18:19], 0, v[128:129]
	v_readfirstlane_b32 s18, v163
	v_lshl_add_u64 v[140:141], v[140:141], 0, s[46:47]
	s_mov_b32 m0, s18
	s_nop 0
	global_load_lds_dwordx4 v[140:141], off
	s_barrier
	s_waitcnt lgkmcnt(0)
	s_setprio 1
	s_waitcnt lgkmcnt(0)
	v_mfma_f32_16x16x32_bf16 v[124:127], v[152:155], v[176:179], v[124:127]
	v_mfma_f32_16x16x32_bf16 v[116:119], v[152:155], v[186:189], v[116:119]
	v_mfma_f32_16x16x32_bf16 v[108:111], v[152:155], v[194:197], v[108:111]
	v_mfma_f32_16x16x32_bf16 v[100:103], v[152:155], v[202:205], v[100:103]
	v_mfma_f32_16x16x32_bf16 v[124:127], v[164:167], v[182:185], v[124:127]
	v_mfma_f32_16x16x32_bf16 v[120:123], v[168:171], v[176:179], v[120:123]
	v_mfma_f32_16x16x32_bf16 v[116:119], v[164:167], v[190:193], v[116:119]
	v_mfma_f32_16x16x32_bf16 v[112:115], v[168:171], v[186:189], v[112:115]
	v_mfma_f32_16x16x32_bf16 v[108:111], v[164:167], v[198:201], v[108:111]
	v_mfma_f32_16x16x32_bf16 v[104:107], v[168:171], v[194:197], v[104:107]
	v_mfma_f32_16x16x32_bf16 v[100:103], v[164:167], v[206:209], v[100:103]
	v_mfma_f32_16x16x32_bf16 v[96:99], v[168:171], v[202:205], v[96:99]
	v_mfma_f32_16x16x32_bf16 v[210:213], v[172:175], v[182:185], v[120:123]
	v_mfma_f32_16x16x32_bf16 v[214:217], v[172:175], v[190:193], v[112:115]
	s_setprio 2
	s_barrier
	v_mfma_f32_16x16x32_bf16 v[218:221], v[172:175], v[198:201], v[104:107]
	v_mfma_f32_16x16x32_bf16 v[230:233], v[172:175], v[206:209], v[96:99]
	s_setprio 0
	s_nop 1
	ds_read_b128 v[96:99], v150 offset:16384
	ds_read_b128 v[104:107], v150 offset:17408
	ds_read_b128 v[112:115], v150 offset:18432
	ds_read_b128 v[120:123], v150 offset:19456
	s_barrier
	s_waitcnt lgkmcnt(0)
	s_setprio 1
	s_waitcnt lgkmcnt(0)
	v_mfma_f32_16x16x32_bf16 v[92:95], v[96:99], v[176:179], v[92:95]
	v_mfma_f32_16x16x32_bf16 v[84:87], v[96:99], v[186:189], v[84:87]
	v_mfma_f32_16x16x32_bf16 v[76:79], v[96:99], v[194:197], v[76:79]
	v_mfma_f32_16x16x32_bf16 v[68:71], v[96:99], v[202:205], v[68:71]
	v_mfma_f32_16x16x32_bf16 v[92:95], v[104:107], v[182:185], v[92:95]
	v_mfma_f32_16x16x32_bf16 v[88:91], v[112:115], v[176:179], v[88:91]
	v_mfma_f32_16x16x32_bf16 v[84:87], v[104:107], v[190:193], v[84:87]
	v_mfma_f32_16x16x32_bf16 v[80:83], v[112:115], v[186:189], v[80:83]
	v_mfma_f32_16x16x32_bf16 v[76:79], v[104:107], v[198:201], v[76:79]
	v_mfma_f32_16x16x32_bf16 v[72:75], v[112:115], v[194:197], v[72:75]
	v_mfma_f32_16x16x32_bf16 v[68:71], v[104:107], v[206:209], v[68:71]
	v_mfma_f32_16x16x32_bf16 v[64:67], v[112:115], v[202:205], v[64:67]
	v_mfma_f32_16x16x32_bf16 v[176:179], v[120:123], v[182:185], v[88:91]
	v_mfma_f32_16x16x32_bf16 v[182:185], v[120:123], v[190:193], v[80:83]
	s_setprio 2
	s_barrier
	v_mfma_f32_16x16x32_bf16 v[186:189], v[120:123], v[198:201], v[72:75]
	v_mfma_f32_16x16x32_bf16 v[190:193], v[120:123], v[206:209], v[64:67]
	s_setprio 0
	s_nop 1
	ds_read_b128 v[64:67], v149 offset:16384
	ds_read_b128 v[72:75], v149 offset:17408
	ds_read_b128 v[80:83], v149 offset:18432
	ds_read_b128 v[88:91], v149 offset:19456
	ds_read_b128 v[194:197], v149 offset:20480
	ds_read_b128 v[198:201], v149 offset:21504
	ds_read_b128 v[202:205], v149 offset:22528
	ds_read_b128 v[206:209], v149 offset:23552
	s_waitcnt vmcnt(4)
	s_barrier
; #define STAGE_A(P, br, kt) do { const char* _base = (const char*)(((kt) < G.ksplit ? G.A1 : A2m) + (long)(br) * G.lda + (long)(kt) * BK); \
;     __builtin_amdgcn_global_load_lds((const unsigned*)(_base + aoff0), (unsigned*)((char*)(P) + sb0), 16, 0, 0); \
;     __builtin_amdgcn_global_load_lds((const unsigned*)(_base + aoff1), (unsigned*)((char*)(P) + sb1), 16, 0, 0); } while (0)
; #define LDA(dst, b, h) for (int m = 0; m < 4; ++m) for (int k = 0; k < 2; ++k) \
;     dst[m][k] = *reinterpret_cast<const bf16x8*>(a_rd + ((b) * 2 + (h)) * (HT * 2) + m * 2048 + k * 1024)
; #define LDB(dst, b, h) for (int n = 0; n < 2; ++n) for (int k = 0; k < 2; ++k) \
;     dst[n][k] = *reinterpret_cast<const bf16x8*>(b_rd + ((b) * 2 + (h)) * (HT * 2) + n * 2048 + k * 1024)
; #define MMA(ai, bj, At_, Bt_) do { __builtin_amdgcn_s_setprio(1); \
;     for (int m = 0; m < 4; ++m) for (int n = 0; n < 2; ++n) for (int k = 0; k < 2; ++k) \
;       acc[ai][bj][m][n] = __builtin_amdgcn_mfma_f32_16x16x32_bf16(Bt_[n][k], At_[m][k], acc[ai][bj][m][n], 0, 0, 0); \
;     __builtin_amdgcn_s_setprio(0); } while (0)
; #define WAIT_V(n) asm volatile("s_waitcnt vmcnt(" #n ")" ::: "memory")
; #define WAIT_L(n) asm volatile("s_waitcnt lgkmcnt(" #n ")" ::: "memory")
; #define BAR __builtin_amdgcn_s_barrier()
;     ...
;   { LDB(B0, 0, 0); LDA(At, 0, 0); STAGE_A(SA(1, 1), brow + HALF, nt - 1);
;     BAR; WAIT_L(0); MMA(0, 0, At, B0); BAR;
;     LDB(B1, 0, 1); BAR; WAIT_L(0); MMA(0, 1, At, B1); BAR;
;     LDA(At, 0, 1); WAIT_V(4); BAR; WAIT_L(0); MMA(1, 0, At, B0); MMA(1, 1, At, B1); BAR; }
;   { LDB(B0, 1, 0); LDA(At, 1, 0); WAIT_V(2); BAR; WAIT_L(0); MMA(0, 0, At, B0); BAR;
;     LDB(B1, 1, 1); WAIT_V(0); BAR; WAIT_L(0); MMA(0, 1, At, B1); BAR;
;     LDA(At, 1, 1); BAR; WAIT_L(0); MMA(1, 0, At, B0); MMA(1, 1, At, B1); BAR; }
	s_waitcnt lgkmcnt(0)
	s_setprio 1
	s_waitcnt lgkmcnt(0)
	v_mfma_f32_16x16x32_bf16 v[60:63], v[152:155], v[64:67], v[60:63]
	v_mfma_f32_16x16x32_bf16 v[52:55], v[152:155], v[80:83], v[52:55]
	v_mfma_f32_16x16x32_bf16 v[44:47], v[152:155], v[194:197], v[44:47]
	v_mfma_f32_16x16x32_bf16 v[36:39], v[152:155], v[202:205], v[36:39]
	v_mfma_f32_16x16x32_bf16 v[60:63], v[164:167], v[72:75], v[60:63]
	v_mfma_f32_16x16x32_bf16 v[56:59], v[168:171], v[64:67], v[56:59]
	v_mfma_f32_16x16x32_bf16 v[52:55], v[164:167], v[88:91], v[52:55]
	v_mfma_f32_16x16x32_bf16 v[48:51], v[168:171], v[80:83], v[48:51]
	v_mfma_f32_16x16x32_bf16 v[44:47], v[164:167], v[198:201], v[44:47]
	v_mfma_f32_16x16x32_bf16 v[40:43], v[168:171], v[194:197], v[40:43]
	v_mfma_f32_16x16x32_bf16 v[36:39], v[164:167], v[206:209], v[36:39]
	v_mfma_f32_16x16x32_bf16 v[32:35], v[168:171], v[202:205], v[32:35]
	v_mfma_f32_16x16x32_bf16 v[238:241], v[172:175], v[72:75], v[56:59]
	v_mfma_f32_16x16x32_bf16 v[246:249], v[172:175], v[88:91], v[48:51]
	v_mfma_f32_16x16x32_bf16 v[234:237], v[172:175], v[198:201], v[40:43]
	v_mfma_f32_16x16x32_bf16 v[152:155], v[172:175], v[206:209], v[32:35]
	s_setprio 0
	s_setprio 1
	v_mfma_f32_16x16x32_bf16 v[28:31], v[96:99], v[64:67], v[28:31]
	v_mfma_f32_16x16x32_bf16 v[20:23], v[96:99], v[80:83], v[20:23]
	v_mfma_f32_16x16x32_bf16 v[12:15], v[96:99], v[194:197], v[12:15]
	v_mfma_f32_16x16x32_bf16 v[4:7], v[96:99], v[202:205], v[4:7]
	v_mfma_f32_16x16x32_bf16 v[28:31], v[104:107], v[72:75], v[28:31]
	v_mfma_f32_16x16x32_bf16 v[24:27], v[112:115], v[64:67], v[24:27]
	v_mfma_f32_16x16x32_bf16 v[20:23], v[104:107], v[88:91], v[20:23]
	v_mfma_f32_16x16x32_bf16 v[16:19], v[112:115], v[80:83], v[16:19]
	v_mfma_f32_16x16x32_bf16 v[12:15], v[104:107], v[198:201], v[12:15]
	v_mfma_f32_16x16x32_bf16 v[8:11], v[112:115], v[194:197], v[8:11]
	v_mfma_f32_16x16x32_bf16 v[4:7], v[104:107], v[206:209], v[4:7]
	v_mfma_f32_16x16x32_bf16 v[0:3], v[112:115], v[202:205], v[0:3]
	v_mfma_f32_16x16x32_bf16 v[162:165], v[120:123], v[72:75], v[24:27]
	v_mfma_f32_16x16x32_bf16 v[166:169], v[120:123], v[88:91], v[16:19]
	s_setprio 2
	s_barrier
	v_mfma_f32_16x16x32_bf16 v[170:173], v[120:123], v[198:201], v[8:11]
	v_mfma_f32_16x16x32_bf16 v[194:197], v[120:123], v[206:209], v[0:3]
	s_setprio 0
	s_nop 1
	ds_read_b128 v[0:3], v150 offset:32768
	ds_read_b128 v[8:11], v150 offset:33792
	ds_read_b128 v[16:19], v150 offset:34816
	ds_read_b128 v[24:27], v150 offset:35840
	ds_read_b128 v[32:35], v149 offset:32768
	ds_read_b128 v[40:43], v149 offset:33792
	ds_read_b128 v[48:51], v149 offset:34816
	ds_read_b128 v[56:59], v149 offset:35840
	ds_read_b128 v[64:67], v149 offset:36864
	ds_read_b128 v[198:201], v149 offset:37888
	ds_read_b128 v[202:205], v149 offset:38912
	ds_read_b128 v[206:209], v149 offset:39936
	s_waitcnt vmcnt(2)
	s_barrier
	s_waitcnt lgkmcnt(0)
	s_setprio 1
	s_waitcnt lgkmcnt(0)
	v_mfma_f32_16x16x32_bf16 v[72:75], v[0:3], v[32:35], v[124:127]
	v_mfma_f32_16x16x32_bf16 v[120:123], v[8:11], v[40:43], v[72:75]
	v_mfma_f32_16x16x32_bf16 v[72:75], v[16:19], v[32:35], v[210:213]
	v_mfma_f32_16x16x32_bf16 v[124:127], v[24:27], v[40:43], v[72:75]
	v_mfma_f32_16x16x32_bf16 v[72:75], v[0:3], v[48:51], v[116:119]
	v_mfma_f32_16x16x32_bf16 v[112:115], v[8:11], v[56:59], v[72:75]
	v_mfma_f32_16x16x32_bf16 v[72:75], v[16:19], v[48:51], v[214:217]
	v_mfma_f32_16x16x32_bf16 v[116:119], v[24:27], v[56:59], v[72:75]
	v_mfma_f32_16x16x32_bf16 v[72:75], v[0:3], v[64:67], v[108:111]
	v_mfma_f32_16x16x32_bf16 v[104:107], v[8:11], v[198:201], v[72:75]
	v_mfma_f32_16x16x32_bf16 v[72:75], v[16:19], v[64:67], v[218:221]
	v_mfma_f32_16x16x32_bf16 v[108:111], v[24:27], v[198:201], v[72:75]
	v_mfma_f32_16x16x32_bf16 v[72:75], v[0:3], v[202:205], v[100:103]
	v_mfma_f32_16x16x32_bf16 v[96:99], v[8:11], v[206:209], v[72:75]
	s_setprio 2
	s_barrier
	v_mfma_f32_16x16x32_bf16 v[72:75], v[16:19], v[202:205], v[230:233]
	v_mfma_f32_16x16x32_bf16 v[100:103], v[24:27], v[206:209], v[72:75]
	s_setprio 0
	ds_read_b128 v[210:213], v150 offset:49152
	ds_read_b128 v[214:217], v150 offset:50176
	ds_read_b128 v[218:221], v150 offset:51200
	ds_read_b128 v[230:233], v150 offset:52224
	s_waitcnt vmcnt(0)
	s_barrier
	s_waitcnt lgkmcnt(0)
	s_setprio 1
	s_waitcnt lgkmcnt(0)
	v_mfma_f32_16x16x32_bf16 v[72:75], v[210:213], v[32:35], v[92:95]
	v_mfma_f32_16x16x32_bf16 v[32:35], v[218:221], v[32:35], v[176:179]
	v_mfma_f32_16x16x32_bf16 v[92:95], v[230:233], v[40:43], v[32:35]
	v_mfma_f32_16x16x32_bf16 v[32:35], v[210:213], v[48:51], v[84:87]
	v_mfma_f32_16x16x32_bf16 v[80:83], v[214:217], v[56:59], v[32:35]
	v_mfma_f32_16x16x32_bf16 v[32:35], v[218:221], v[48:51], v[182:185]
	v_mfma_f32_16x16x32_bf16 v[84:87], v[230:233], v[56:59], v[32:35]
	v_mfma_f32_16x16x32_bf16 v[32:35], v[210:213], v[64:67], v[76:79]
	v_mfma_f32_16x16x32_bf16 v[88:91], v[214:217], v[40:43], v[72:75]
	v_mfma_f32_16x16x32_bf16 v[72:75], v[214:217], v[198:201], v[32:35]
	v_mfma_f32_16x16x32_bf16 v[32:35], v[218:221], v[64:67], v[186:189]
	v_mfma_f32_16x16x32_bf16 v[76:79], v[230:233], v[198:201], v[32:35]
	v_mfma_f32_16x16x32_bf16 v[32:35], v[210:213], v[202:205], v[68:71]
	v_mfma_f32_16x16x32_bf16 v[64:67], v[214:217], v[206:209], v[32:35]
	s_setprio 2
	s_barrier
; #define STAGE_A(P, br, kt) do { const char* _base = (const char*)(((kt) < G.ksplit ? G.A1 : A2m) + (long)(br) * G.lda + (long)(kt) * BK); \
;     __builtin_amdgcn_global_load_lds((const unsigned*)(_base + aoff0), (unsigned*)((char*)(P) + sb0), 16, 0, 0); \
;     __builtin_amdgcn_global_load_lds((const unsigned*)(_base + aoff1), (unsigned*)((char*)(P) + sb1), 16, 0, 0); } while (0)
; #define STAGE_B(P, br, kt) do { const char* _base = (const char*)(G.Bt + (long)(br) * G.ldb + (long)(kt) * BK); \
;     __builtin_amdgcn_global_load_lds((const unsigned*)(_base + boff0), (unsigned*)((char*)(P) + sb0), 16, 0, 0); \
;     __builtin_amdgcn_global_load_lds((const unsigned*)(_base + boff1), (unsigned*)((char*)(P) + sb1), 16, 0, 0); } while (0)
; #define LDA(dst, b, h) for (int m = 0; m < 4; ++m) for (int k = 0; k < 2; ++k) \
;     dst[m][k] = *reinterpret_cast<const bf16x8*>(a_rd + ((b) * 2 + (h)) * (HT * 2) + m * 2048 + k * 1024)
; #define LDB(dst, b, h) for (int n = 0; n < 2; ++n) for (int k = 0; k < 2; ++k) \
;     dst[n][k] = *reinterpret_cast<const bf16x8*>(b_rd + ((b) * 2 + (h)) * (HT * 2) + n * 2048 + k * 1024)
; #define MMA(ai, bj, At_, Bt_) do { __builtin_amdgcn_s_setprio(1); \
;     for (int m = 0; m < 4; ++m) for (int n = 0; n < 2; ++n) for (int k = 0; k < 2; ++k) \
;       acc[ai][bj][m][n] = __builtin_amdgcn_mfma_f32_16x16x32_bf16(Bt_[n][k], At_[m][k], acc[ai][bj][m][n], 0, 0, 0); \
;     __builtin_amdgcn_s_setprio(0); } while (0)
; #define WAIT_V(n) asm volatile("s_waitcnt vmcnt(" #n ")" ::: "memory")
; #define WAIT_L(n) asm volatile("s_waitcnt lgkmcnt(" #n ")" ::: "memory")
; #define BAR __builtin_amdgcn_s_barrier()
;     ...
;   { LDB(B0, 1, 0); LDA(At, 1, 0); WAIT_V(2); BAR; WAIT_L(0); MMA(0, 0, At, B0); BAR;
;     LDB(B1, 1, 1); WAIT_V(0); BAR; WAIT_L(0); MMA(0, 1, At, B1); BAR;
;     LDA(At, 1, 1); BAR; WAIT_L(0); MMA(1, 0, At, B0); MMA(1, 1, At, B1); BAR; }
;   if (wr == 0) BAR;
;   if (EPI != EPI_RESID && has_next) {
;     STAGE_B(SB(0, 0), nbcol, 0); STAGE_A(SA(0, 0), nbrow, 0);
;     STAGE_B(SB(0, 1), nbcol + HALF, 0); STAGE_A(SA(0, 1), nbrow + HALF, 0);
;   }
	v_mfma_f32_16x16x32_bf16 v[32:35], v[218:221], v[202:205], v[190:193]
	v_mfma_f32_16x16x32_bf16 v[68:71], v[230:233], v[206:209], v[32:35]
	s_setprio 0
	ds_read_b128 v[174:177], v149 offset:49152
	ds_read_b128 v[182:185], v149 offset:50176
	ds_read_b128 v[186:189], v149 offset:51200
	ds_read_b128 v[190:193], v149 offset:52224
	ds_read_b128 v[198:201], v149 offset:53248
	ds_read_b128 v[202:205], v149 offset:54272
	ds_read_b128 v[206:209], v149 offset:55296
	ds_read_b128 v[148:151], v149 offset:56320
	s_barrier
	s_waitcnt lgkmcnt(0)
	v_readfirstlane_b32 s18, v224
	s_setprio 1
	s_waitcnt lgkmcnt(0)
	v_mfma_f32_16x16x32_bf16 v[32:35], v[0:3], v[174:177], v[60:63]
	v_mfma_f32_16x16x32_bf16 v[56:59], v[8:11], v[182:185], v[32:35]
	v_mfma_f32_16x16x32_bf16 v[32:35], v[16:19], v[174:177], v[238:241]
	v_mfma_f32_16x16x32_bf16 v[60:63], v[24:27], v[182:185], v[32:35]
	v_mfma_f32_16x16x32_bf16 v[32:35], v[0:3], v[186:189], v[52:55]
	v_mfma_f32_16x16x32_bf16 v[48:51], v[8:11], v[190:193], v[32:35]
	v_mfma_f32_16x16x32_bf16 v[32:35], v[16:19], v[186:189], v[246:249]
	v_mfma_f32_16x16x32_bf16 v[52:55], v[24:27], v[190:193], v[32:35]
	v_mfma_f32_16x16x32_bf16 v[32:35], v[0:3], v[198:201], v[44:47]
	v_mfma_f32_16x16x32_bf16 v[40:43], v[8:11], v[202:205], v[32:35]
	v_mfma_f32_16x16x32_bf16 v[32:35], v[16:19], v[198:201], v[234:237]
	v_mfma_f32_16x16x32_bf16 v[0:3], v[0:3], v[206:209], v[36:39]
	v_mfma_f32_16x16x32_bf16 v[44:47], v[24:27], v[202:205], v[32:35]
	v_mfma_f32_16x16x32_bf16 v[32:35], v[8:11], v[148:151], v[0:3]
	v_mfma_f32_16x16x32_bf16 v[0:3], v[16:19], v[206:209], v[152:155]
	v_mfma_f32_16x16x32_bf16 v[36:39], v[24:27], v[148:151], v[0:3]
	s_setprio 0
	s_setprio 1
	v_mfma_f32_16x16x32_bf16 v[0:3], v[210:213], v[174:177], v[28:31]
	v_mfma_f32_16x16x32_bf16 v[24:27], v[214:217], v[182:185], v[0:3]
	v_mfma_f32_16x16x32_bf16 v[0:3], v[218:221], v[174:177], v[162:165]
	v_mfma_f32_16x16x32_bf16 v[28:31], v[230:233], v[182:185], v[0:3]
	v_mfma_f32_16x16x32_bf16 v[0:3], v[210:213], v[186:189], v[20:23]
	v_mfma_f32_16x16x32_bf16 v[16:19], v[214:217], v[190:193], v[0:3]
	v_mfma_f32_16x16x32_bf16 v[0:3], v[218:221], v[186:189], v[166:169]
	v_mfma_f32_16x16x32_bf16 v[20:23], v[230:233], v[190:193], v[0:3]
	v_mfma_f32_16x16x32_bf16 v[0:3], v[210:213], v[198:201], v[12:15]
	v_mfma_f32_16x16x32_bf16 v[8:11], v[214:217], v[202:205], v[0:3]
	v_mfma_f32_16x16x32_bf16 v[0:3], v[218:221], v[198:201], v[170:173]
	v_mfma_f32_16x16x32_bf16 v[12:15], v[230:233], v[202:205], v[0:3]
	v_mfma_f32_16x16x32_bf16 v[0:3], v[210:213], v[206:209], v[4:7]
	v_mfma_f32_16x16x32_bf16 v[4:7], v[218:221], v[206:209], v[194:197]
	s_setprio 2
	s_bitcmp0_b32 s18, 8
	s_cbranch_scc0 .Lmy_gu_t6skip
	s_barrier
.Lmy_gu_t6skip:
	v_mfma_f32_16x16x32_bf16 v[0:3], v[214:217], v[148:151], v[0:3]
	v_mfma_f32_16x16x32_bf16 v[4:7], v[230:233], v[148:151], v[4:7]
	s_setprio 0
	s_andn2_b64 vcc, exec, s[16:17]
	v_mov_b32_e32 v249, v245
	s_cbranch_vccnz .LBB0_2558
	s_mul_i32 s16, s27, 0x840
	s_ashr_i32 s17, s16, 31
	s_lshl_b64 s[16:17], s[16:17], 1
	s_add_u32 s16, s8, s16
	s_addc_u32 s17, s9, s17
	v_readfirstlane_b32 s18, v159
	v_lshl_add_u64 v[140:141], s[16:17], 0, v[180:181]
	s_mov_b32 m0, s18
	s_mul_i32 s18, s26, 0x1080
	global_load_lds_dwordx4 v[140:141], off
	v_lshl_add_u64 v[140:141], s[16:17], 0, v[128:129]
	v_readfirstlane_b32 s16, v160
	s_mov_b32 m0, s16
	s_mul_hi_i32 s17, s26, 0x1080
	s_add_u32 s16, s23, s18
	s_addc_u32 s17, s24, s17
	v_readfirstlane_b32 s19, v147
	global_load_lds_dwordx4 v[140:141], off
	v_lshl_add_u64 v[140:141], s[16:17], 0, v[180:181]
	s_mov_b32 m0, s19
	v_readfirstlane_b32 s19, v145
	global_load_lds_dwordx4 v[140:141], off
	v_lshl_add_u64 v[140:141], s[16:17], 0, v[128:129]
	v_readfirstlane_b32 s16, v146
	s_mov_b32 m0, s16
	s_or_b32 s16, s27, 0x80
	s_mul_hi_i32 s17, s16, 0x1080
	s_mulk_i32 s16, 0x1080
	s_add_u32 s16, s8, s16
	s_addc_u32 s17, s9, s17
	global_load_lds_dwordx4 v[140:141], off
	v_lshl_add_u64 v[140:141], s[16:17], 0, v[180:181]
	s_mov_b32 m0, s19
	s_add_i32 s18, s18, 0x84000
	global_load_lds_dwordx4 v[140:141], off
	v_lshl_add_u64 v[140:141], s[16:17], 0, v[128:129]
	v_readfirstlane_b32 s16, v161
	s_mov_b32 m0, s16
	s_add_i32 s16, s26, 0x80
	s_mul_hi_i32 s17, s16, 0x1080
	s_add_u32 s16, s23, s18
	s_addc_u32 s17, s24, s17
	v_readfirstlane_b32 s18, v143
	global_load_lds_dwordx4 v[140:141], off
	v_lshl_add_u64 v[140:141], s[16:17], 0, v[180:181]
	s_mov_b32 m0, s18
	v_lshl_add_u64 v[128:129], s[16:17], 0, v[128:129]
	v_readfirstlane_b32 s16, v142
	global_load_lds_dwordx4 v[140:141], off
	s_mov_b32 m0, s16
	s_nop 0
	global_load_lds_dwordx4 v[128:129], off
	s_branch .LBB0_2558
